# attention V^T LDS tile: 8-byte swizzle by row bit4 + ds_read_b64 instead of ds_read2_b64 (bank-conflict-free V fragment reads)
# speedup vs baseline: 1.0096x; 1.0096x over previous
; DI int fresh_tid(const Params& p) { int t = p.wave_u * 64 + (int)__builtin_amdgcn_mbcnt_hi(~0u, __builtin_amdgcn_mbcnt_lo(~0u, 0u)); asm volatile("" : "+v"(t)); return t; }
; DI void attn_item(const Params& p, int bh, int qb, unsigned char* smem) {
;     ...
;     const int qrow = qb * 256 + wave * 32 + r;
;     const bf16_t* Qg = (const bf16_t*)(p.ws + WS_Q) + ((size_t)bh * SEQ_ + qrow) * 192;
;     const bf16_t* Kg = (const bf16_t*)(p.ws + WS_K) + (size_t)bh * SEQ_ * 192;
;     const bf16_t* Vg = (const bf16_t*)(p.ws + WS_VT) + (size_t)bh * 128 * SEQ_;
;     bf16x8 qf[12];
; #pragma unroll
;     for (int ks = 0; ks < 12; ++ks) qf[ks] = *(const bf16x8*)(Qg + ks * 16 + h * 8);
;     f32x16 O[4];
; #pragma unroll
;     for (int t = 0; t < 4; ++t) zero_acc(O[t]);
;     float m_run = -INFINITY, l_run = 0.f;
;     const int ntiles = 4 * qb + 4;
;     const int wrow0 = qb * 256 + wave * 32;
;     u32x4 rk[3], rv[2];
;     ...
;     KV_LOAD(0);
;     __syncthreads();
;     KV_STORE(0);
;     if (ntiles > 1) KV_LOAD(1);
;     __syncthreads();
; DI void phase3(const Params& p, unsigned char* smem, unsigned char* smem_wg, int* s_item) {
;     ...
;         if ((p.vb & 1) == 0 && fresh_tid(p) == 0) *s_item = (int)atomicAdd(ctr, 1u);
;         __syncthreads();
;         const int item = *s_item;
;         __syncthreads();
;         if (item >= 1024) break;
.LBB0_446:
	s_waitcnt lgkmcnt(0)
	s_barrier
	ds_read_b32 v0, v162
	s_movk_i32 s6, 0x3ff
	s_waitcnt lgkmcnt(0)
	s_barrier
	v_cmp_lt_i32_e32 vcc, s6, v0
	v_readfirstlane_b32 s8, v0
	s_mov_b64 s[6:7], -1
	s_cbranch_vccnz .LBB0_439
	s_lshr_b32 s98, s86, 4
	s_and_b32 s98, s98, 8
	s_ashr_i32 s44, s8, 5
	s_sub_i32 s63, 31, s44
	v_mov_b32_e32 v1, v227
	s_lshl_b32 s62, s63, 8
	s_add_i32 s62, s62, s78
	v_and_b32_e32 v182, 31, v1
	s_and_b32 s61, s8, 31
	v_or_b32_e32 v164, s62, v182
	v_bfe_u32 v0, v1, 5, 1
	v_lshl_add_u32 v4, s61, 13, v164
	v_mov_b64_e32 v[2:3], s[46:47]
	v_mad_u64_u32 v[2:3], s[6:7], v4, s56, v[2:3]
	v_lshlrev_b32_e32 v148, 4, v0
	v_lshl_add_u64 v[2:3], v[2:3], 0, v[148:149]
	v_and_or_b32 v14, v1, 63, s86
	global_load_dwordx4 v[80:83], v[2:3], off
	global_load_dwordx4 v[84:87], v[2:3], off offset:32
	global_load_dwordx4 v[88:91], v[2:3], off offset:64
	global_load_dwordx4 v[92:95], v[2:3], off offset:96
	global_load_dwordx4 v[96:99], v[2:3], off offset:128
	global_load_dwordx4 v[100:103], v[2:3], off offset:160
	global_load_dwordx4 v[104:107], v[2:3], off offset:192
	global_load_dwordx4 v[108:111], v[2:3], off offset:224
	global_load_dwordx4 v[112:115], v[2:3], off offset:256
	global_load_dwordx4 v[116:119], v[2:3], off offset:288
	global_load_dwordx4 v[120:123], v[2:3], off offset:320
	global_load_dwordx4 v[124:127], v[2:3], off offset:352
	v_mul_hi_i32 v2, v14, s57
	v_lshrrev_b32_e32 v3, 31, v2
	v_ashrrev_i32_e32 v2, 2, v2
	v_add_u32_e32 v18, 0x200, v14
	v_add_u32_e32 v10, 0x400, v14
	s_mul_i32 s6, s61, 0x300000
	v_add_u32_e32 v165, v2, v3
	v_mul_hi_i32 v6, v18, s57
	v_mul_hi_i32 v11, v10, s57
	s_add_u32 s6, s48, s6
	v_mul_lo_u32 v2, v165, 24
	v_lshrrev_b32_e32 v7, 31, v6
	v_ashrrev_i32_e32 v6, 2, v6
	v_lshrrev_b32_e32 v12, 31, v11
	v_ashrrev_i32_e32 v11, 2, v11
	s_addc_u32 s7, s49, 0
	v_sub_u32_e32 v56, v14, v2
	v_add_u32_e32 v166, v6, v7
	v_add_u32_e32 v167, v11, v12
	v_mov_b64_e32 v[30:31], s[6:7]
	v_lshlrev_b32_e32 v4, 3, v56
	v_mul_lo_u32 v6, v166, 24
	v_mul_lo_u32 v11, v167, 24
	s_lshl_b32 s10, s61, 21
	v_mad_i64_i32 v[2:3], s[8:9], v165, s56, v[30:31]
	v_ashrrev_i32_e32 v5, 31, v4
	v_sub_u32_e32 v57, v18, v6
	v_mad_i64_i32 v[6:7], s[8:9], v166, s56, v[30:31]
	v_sub_u32_e32 v58, v10, v11
	v_mad_i64_i32 v[10:11], s[8:9], v167, s56, v[30:31]
	v_lshlrev_b32_e32 v1, 3, v1
	v_lshlrev_b64 v[42:43], 1, v[4:5]
	v_lshlrev_b32_e32 v8, 3, v57
	v_lshlrev_b32_e32 v12, 3, v58
	s_add_u32 s8, s50, s10
	v_and_b32_e32 v168, 56, v1
	v_ashrrev_i32_e32 v50, 3, v14
	v_ashrrev_i32_e32 v54, 3, v18
	v_lshl_add_u64 v[2:3], v[2:3], 0, v[42:43]
	v_ashrrev_i32_e32 v9, 31, v8
	v_ashrrev_i32_e32 v13, 31, v12
	s_addc_u32 s9, s51, 0
	v_lshlrev_b32_e32 v48, 1, v168
	v_mov_b32_e32 v49, v149
	v_ashrrev_i32_e32 v51, 31, v50
	v_ashrrev_i32_e32 v55, 31, v54
	v_add_u32_e32 v1, 64, v165
	global_load_dwordx4 v[2:5], v[2:3], off
	v_lshlrev_b64 v[44:45], 1, v[8:9]
	v_lshlrev_b64 v[46:47], 1, v[12:13]
	v_lshl_add_u64 v[150:151], s[8:9], 0, v[48:49]
	v_lshlrev_b64 v[152:153], 14, v[50:51]
	v_lshlrev_b64 v[154:155], 14, v[54:55]
	v_mad_i64_i32 v[22:23], s[10:11], v1, s56, v[30:31]
	v_add_u32_e32 v1, 64, v166
	v_lshl_add_u64 v[6:7], v[6:7], 0, v[44:45]
	v_lshl_add_u64 v[10:11], v[10:11], 0, v[46:47]
	v_lshl_add_u64 v[52:53], v[150:151], 0, v[152:153]
	v_lshl_add_u64 v[72:73], v[150:151], 0, v[154:155]
	v_lshl_add_u64 v[22:23], v[22:23], 0, v[42:43]
	v_mad_i64_i32 v[26:27], s[10:11], v1, s56, v[30:31]
	v_add_u32_e32 v1, 64, v167
	global_load_dwordx4 v[6:9], v[6:7], off
	v_lshl_add_u64 v[26:27], v[26:27], 0, v[44:45]
	global_load_dwordx4 v[10:13], v[10:11], off
	v_mad_i64_i32 v[30:31], s[10:11], v1, s56, v[30:31]
	global_load_dwordx4 v[14:17], v[52:53], off
	global_load_dwordx4 v[18:21], v[72:73], off
	s_barrier
	global_load_dwordx4 v[22:25], v[22:23], off
	v_lshl_add_u64 v[34:35], s[8:9], 0, v[152:153]
	v_lshl_add_u64 v[38:39], s[8:9], 0, v[154:155]
	global_load_dwordx4 v[26:29], v[26:27], off
	v_lshl_add_u64 v[30:31], v[30:31], 0, v[46:47]
	v_lshl_add_u64 v[34:35], v[34:35], 0, v[48:49]
	v_lshl_add_u64 v[38:39], v[38:39], 0, v[48:49]
	global_load_dwordx4 v[30:33], v[30:31], off
	v_mul_lo_u32 v169, v165, s58
	global_load_dwordx4 v[34:37], v[34:35], off offset:128
	v_lshlrev_b32_e32 v170, 4, v56
	global_load_dwordx4 v[38:41], v[38:39], off offset:128
	v_add3_u32 v1, 0, v169, v170
	v_mul_lo_u32 v171, v166, s58
	v_lshlrev_b32_e32 v172, 4, v57
	v_mul_lo_u32 v173, v167, s58
	v_lshlrev_b32_e32 v174, 4, v58
	v_mul_lo_u32 v175, v50, s59
	v_mul_lo_u32 v176, v54, s59
	v_lshl_add_u64 v[156:157], s[6:7], 0, v[42:43]
	v_lshl_add_u64 v[158:159], s[6:7], 0, v[44:45]
	v_lshl_add_u64 v[160:161], s[6:7], 0, v[46:47]
	v_lshlrev_b32_e32 v177, 2, v0
	v_cmp_gt_u32_e32 vcc, v177, v182
	s_cmp_lg_u32 s62, 0
	s_waitcnt vmcnt(9)
	ds_write_b128 v1, v[2:5]
	v_add_u32_e32 v4, 0, v48
	v_add3_u32 v2, 0, v171, v172
	v_add3_u32 v3, 0, v173, v174
	v_add_u32_e32 v5, v4, v175
	v_add_u32_e32 v4, v4, v176
	s_waitcnt vmcnt(8)
	ds_write_b128 v2, v[6:9]
	s_waitcnt vmcnt(7)
	ds_write_b128 v3, v[10:13]
	v_add_u32_e32 v186, s98, v5
	v_subrev_u32_e32 v187, s98, v5
	v_add_u32_e32 v188, s98, v4
	v_subrev_u32_e32 v189, s98, v4
	s_waitcnt vmcnt(6)
	ds_write_b64 v186, v[14:15] offset:25600
	ds_write_b64 v187, v[16:17] offset:25608
	s_waitcnt vmcnt(5)
	ds_write_b64 v188, v[18:19] offset:25600
	ds_write_b64 v189, v[20:21] offset:25608
	s_waitcnt lgkmcnt(0)
	s_barrier
; #define MFMA(a, b, c) __builtin_amdgcn_mfma_f32_32x32x16_bf16((a), (b), (c), 0, 0, 0)
; DI int crow(int e, int h) { return (e & 3) + 8 * (e >> 2) + 4 * h; }
; DI void attn_item(const Params& p, int bh, int qb, unsigned char* smem) {
;     ...
;     KV_LOAD(0);
;     __syncthreads();
;     KV_STORE(0);
;     if (ntiles > 1) KV_LOAD(1);
;     __syncthreads();
;     for (int jt = 0; jt < ntiles; ++jt) {
;         if (jt + 1 < ntiles) KV_STORE((jt + 1) & 1);
;         if (jt + 2 < ntiles) KV_LOAD(jt + 2);
; #pragma unroll
;         for (int mt = 0; mt < 2; ++mt) {
;         const int key0 = jt * 64 + mt * 32;
;         if (key0 <= wrow0) {
;             const bf16_t* sK = sbase + (jt & 1) * STG + mt * 32 * 200; const bf16_t* sV = sbase + (jt & 1) * STG + KST + mt * 32;
;             f32x16 sc; zero_acc(sc);
;             {
;                 bf16x8 kf[12];
; #pragma unroll
;                 for (int ks = 0; ks < 12; ++ks) kf[ks] = *(const bf16x8*)(sK + r * 200 + ks * 16 + h * 8);
; #pragma unroll
;                 for (int ks = 0; ks < 12; ++ks) sc = MFMA(kf[ks], qf[ks], sc);
;                 __builtin_amdgcn_sched_group_barrier(0x100, 6, 0);
; #pragma unroll
;                 for (int q = 0; q < 6; ++q) { __builtin_amdgcn_sched_group_barrier(0x008, 1, 0); __builtin_amdgcn_sched_group_barrier(0x100, 1, 0); }
;                 __builtin_amdgcn_sched_group_barrier(0x008, 6, 0);
;             }
;             if (key0 == wrow0) {
; #pragma unroll
;                 for (int e = 0; e < 16; ++e) if (key0 + crow(e, h) > qrow) sc[e] = -INFINITY;
	s_waitcnt vmcnt(4)
	ds_write_b128 v1, v[22:25] offset:44032
	v_add_u32_e32 v1, s60, v48
	global_load_dwordx4 v[140:143], v[52:53], off offset:256
	s_waitcnt vmcnt(4)
	ds_write_b128 v2, v[26:29] offset:44032
	v_add_u32_e32 v2, v1, v175
	v_add_u32_e32 v1, v1, v176
	global_load_dwordx4 v[144:147], v[72:73], off offset:256
	s_waitcnt vmcnt(4)
	ds_write_b128 v3, v[30:33] offset:44032
	v_add_u32_e32 v186, s98, v2
	v_subrev_u32_e32 v187, s98, v2
	v_add_u32_e32 v188, s98, v1
	v_subrev_u32_e32 v189, s98, v1
	s_waitcnt vmcnt(3)
	ds_write_b64 v186, v[34:35]
	ds_write_b64 v187, v[36:37] offset:8
	s_waitcnt vmcnt(2)
	ds_write_b64 v188, v[38:39]
	ds_write_b64 v189, v[40:41] offset:8
	v_mad_u32_u24 v1, v182, s58, 0
	v_add_u32_e32 v183, v1, v148
	ds_read_b128 v[2:5], v183
	ds_read_b128 v[6:9], v183 offset:32
	ds_read_b128 v[10:13], v183 offset:64
	ds_read_b128 v[14:17], v183 offset:96
	ds_read_b128 v[18:21], v183 offset:128
	ds_read_b128 v[22:25], v183 offset:160
	s_waitcnt lgkmcnt(5)
	v_mfma_f32_32x32x16_bf16 v[56:71], v[2:5], v[80:83], 0
	ds_read_b128 v[2:5], v183 offset:192
	v_add_u32_e32 v1, 0x80, v165
	v_mad_i64_i32 v[26:27], s[6:7], v1, s56, v[156:157]
	v_add_u32_e32 v1, 0x80, v166
	global_load_dwordx4 v[128:131], v[26:27], off
	v_mad_i64_i32 v[26:27], s[6:7], v1, s56, v[158:159]
	s_waitcnt lgkmcnt(5)
	v_mfma_f32_32x32x16_bf16 v[56:71], v[6:9], v[84:87], v[56:71]
	v_add_u32_e32 v1, 0x80, v167
	global_load_dwordx4 v[132:135], v[26:27], off
	v_mad_i64_i32 v[26:27], s[6:7], v1, s56, v[160:161]
	ds_read_b128 v[6:9], v183 offset:224
	global_load_dwordx4 v[136:139], v[26:27], off
	v_or_b32_e32 v1, s62, v177
	s_waitcnt lgkmcnt(5)
	v_mfma_f32_32x32x16_bf16 v[56:71], v[10:13], v[88:91], v[56:71]
	ds_read_b128 v[10:13], v183 offset:256
	v_cmp_lt_u32_e64 s[6:7], v177, v182
	s_waitcnt lgkmcnt(5)
	v_mfma_f32_32x32x16_bf16 v[56:71], v[14:17], v[92:95], v[56:71]
	ds_read_b128 v[14:17], v183 offset:288
	s_waitcnt lgkmcnt(5)
	v_mfma_f32_32x32x16_bf16 v[56:71], v[18:21], v[96:99], v[56:71]
	ds_read_b128 v[18:21], v183 offset:320
	s_waitcnt lgkmcnt(5)
	v_mfma_f32_32x32x16_bf16 v[56:71], v[22:25], v[100:103], v[56:71]
	ds_read_b128 v[22:25], v183 offset:352
	s_waitcnt lgkmcnt(5)
	v_mfma_f32_32x32x16_bf16 v[56:71], v[2:5], v[104:107], v[56:71]
	v_or_b32_e32 v2, 2, v1
	v_cmp_gt_i32_e64 s[8:9], v2, v164
	v_or_b32_e32 v2, 3, v1
	v_cmp_gt_i32_e64 s[10:11], v2, v164
	v_or_b32_e32 v2, 8, v1
	v_cmp_gt_i32_e64 s[12:13], v2, v164
	v_or_b32_e32 v2, 9, v1
	s_waitcnt lgkmcnt(4)
	v_mfma_f32_32x32x16_bf16 v[56:71], v[6:9], v[108:111], v[56:71]
	v_cmp_gt_i32_e64 s[14:15], v2, v164
	v_or_b32_e32 v2, 10, v1
	v_cmp_gt_i32_e64 s[16:17], v2, v164
	v_or_b32_e32 v2, 11, v1
	v_cmp_gt_i32_e64 s[18:19], v2, v164
	v_or_b32_e32 v2, 16, v1
	v_cmp_gt_i32_e64 s[20:21], v2, v164
	s_waitcnt lgkmcnt(3)
	v_mfma_f32_32x32x16_bf16 v[56:71], v[10:13], v[112:115], v[56:71]
	v_or_b32_e32 v2, 17, v1
	v_cmp_gt_i32_e64 s[22:23], v2, v164
	v_or_b32_e32 v2, 18, v1
	v_cmp_gt_i32_e64 s[24:25], v2, v164
	v_or_b32_e32 v2, 19, v1
	v_cmp_gt_i32_e64 s[26:27], v2, v164
	v_or_b32_e32 v2, 24, v1
	s_waitcnt lgkmcnt(2)
	v_mfma_f32_32x32x16_bf16 v[56:71], v[14:17], v[116:119], v[56:71]
	v_cmp_gt_i32_e64 s[28:29], v2, v164
	v_or_b32_e32 v2, 25, v1
	v_cmp_gt_i32_e64 s[30:31], v2, v164
	v_or_b32_e32 v2, 26, v1
	v_or_b32_e32 v1, 27, v1
	v_cmp_gt_i32_e64 s[34:35], v2, v164
	v_cmp_gt_i32_e64 s[36:37], v1, v164
	s_waitcnt lgkmcnt(1)
	v_mfma_f32_32x32x16_bf16 v[56:71], v[18:21], v[120:123], v[56:71]
	s_waitcnt lgkmcnt(0)
	v_mfma_f32_32x32x16_bf16 v[56:71], v[22:25], v[124:127], v[56:71]
	s_cbranch_scc1 .LBB0_449
	s_nop 10
	v_cndmask_b32_e32 v1, v56, v163, vcc
	v_cndmask_b32_e64 v57, v163, v57, s[6:7]
	v_cndmask_b32_e64 v56, v1, v56, s[6:7]
	v_cndmask_b32_e64 v58, v58, v163, s[8:9]
	v_cndmask_b32_e64 v59, v59, v163, s[10:11]
	v_cndmask_b32_e64 v60, v60, v163, s[12:13]
	v_cndmask_b32_e64 v61, v61, v163, s[14:15]
	v_cndmask_b32_e64 v62, v62, v163, s[16:17]
	v_cndmask_b32_e64 v63, v63, v163, s[18:19]
	v_cndmask_b32_e64 v64, v64, v163, s[20:21]
	v_cndmask_b32_e64 v65, v65, v163, s[22:23]
	v_cndmask_b32_e64 v66, v66, v163, s[24:25]
	v_cndmask_b32_e64 v67, v67, v163, s[26:27]
	v_cndmask_b32_e64 v68, v68, v163, s[28:29]
	v_cndmask_b32_e64 v69, v69, v163, s[30:31]
	v_cndmask_b32_e64 v70, v70, v163, s[34:35]
	v_cndmask_b32_e64 v71, v71, v163, s[36:37]
; #define MFMA(a, b, c) __builtin_amdgcn_mfma_f32_32x32x16_bf16((a), (b), (c), 0, 0, 0)
; DI void attn_item(const Params& p, int bh, int qb, unsigned char* smem) {
;     ...
;             if (jt == 0 && mt == 0) {
;                 float mx = sc[0];
; #pragma unroll
;                 for (int e = 1; e < 16; ++e) mx = fmaxf(mx, sc[e]);
;                 m_run = fmaxf(mx, __shfl_xor(mx, 32));
;             }
;             float ls = 0.f;
; #pragma unroll
;             for (int e = 0; e < 16; ++e) { const float pv = __builtin_amdgcn_exp2f(sc[e] - m_run); sc[e] = pv; ls += pv; }
;             l_run += ls;
;             bf16x8 pf[2]; pf[0] = pack8<0>(sc); pf[1] = pack8<1>(sc);
;             {
;                 bf16x8 vfr[2][4];
; #pragma unroll
;                 for (int s = 0; s < 2; ++s)
; #pragma unroll
;                     for (int t = 0; t < 4; ++t) vfr[s][t] = ld_frag_perm(sV + (t * 32 + r) * 72 + 16 * s + 4 * h);
; #pragma unroll
;                 for (int s = 0; s < 2; ++s)
; #pragma unroll
;                     for (int t = 0; t < 4; ++t) O[t] = MFMA(vfr[s][t], pf[s], O[t]);
;                 __builtin_amdgcn_sched_group_barrier(0x100, 8, 0);
; #pragma unroll
;                 for (int q = 0; q < 4; ++q) { __builtin_amdgcn_sched_group_barrier(0x008, 1, 0); __builtin_amdgcn_sched_group_barrier(0x100, 2, 0); }
;                 __builtin_amdgcn_sched_group_barrier(0x008, 4, 0);
;             }
;         }
.LBB0_449:
	s_nop 10
	v_max_f32_e32 v1, v57, v57
	v_max_f32_e32 v2, v56, v56
	v_max_f32_e32 v1, v2, v1
	v_max3_f32 v1, v1, v58, v59
	v_max3_f32 v1, v1, v60, v61
	v_max3_f32 v1, v1, v62, v63
	v_max3_f32 v1, v1, v64, v65
	v_max3_f32 v1, v1, v66, v67
	v_max3_f32 v1, v1, v68, v69
	v_max3_f32 v1, v1, v70, v71
	ds_bpermute_b32 v2, v241, v1
	v_lshrrev_b32_e32 v178, 1, v227
	v_xor_b32_e32 v178, v178, v227
	v_lshrrev_b32_e32 v178, 1, v178
	v_and_b32_e32 v178, 8, v178
	v_add_u32_e32 v184, 0, v178
	v_mad_u32_u24 v16, v182, s59, v184
	v_add_u32_e32 v8, 0x6000, v16
	s_waitcnt lgkmcnt(0)
	v_max_f32_e32 v0, v2, v2
	v_max_f32_e32 v179, v1, v0
	v_sub_f32_e32 v0, v56, v179
	v_exp_f32_e32 v180, v0
	v_sub_f32_e32 v0, v58, v179
	v_exp_f32_e32 v198, v0
	v_sub_f32_e32 v0, v59, v179
	v_exp_f32_e32 v199, v0
	v_sub_f32_e32 v0, v60, v179
	ds_read_b64 v[4:5], v8 offset:1024
	ds_read_b64 v[6:7], v8 offset:1040
	v_exp_f32_e32 v200, v0
	v_sub_f32_e32 v0, v61, v179
	v_exp_f32_e32 v201, v0
	v_sub_f32_e32 v0, v62, v179
	v_sub_f32_e32 v1, v57, v179
	v_exp_f32_e32 v202, v0
	v_sub_f32_e32 v0, v63, v179
	v_exp_f32_e32 v185, v1
	v_exp_f32_e32 v203, v0
	v_cvt_pk_bf16_f32 v1, v198, v199
	v_cvt_pk_bf16_f32 v2, v200, v201
	v_cvt_pk_bf16_f32 v0, v180, v185
	v_cvt_pk_bf16_f32 v3, v202, v203
	v_add_u32_e32 v17, 0x7000, v16
	v_add_u32_e32 v18, 0x8800, v16
	v_add_u32_e32 v16, 0x9800, v16
	ds_read_b64 v[72:73], v8 offset:1056
	ds_read_b64 v[74:75], v8 offset:1072
	ds_read_b64 v[8:9], v17 offset:1536
	ds_read_b64 v[10:11], v17 offset:1552
	ds_read_b64 v[12:13], v18 offset:0
	ds_read_b64 v[14:15], v18 offset:16
	ds_read_b64 v[76:77], v16 offset:512
	ds_read_b64 v[78:79], v16 offset:528
	ds_read_b64 v[186:187], v17 offset:1568
	ds_read_b64 v[188:189], v17 offset:1584
	ds_read_b64 v[190:191], v18 offset:32
	ds_read_b64 v[192:193], v18 offset:48
	s_waitcnt lgkmcnt(12)
	v_mfma_f32_32x32x16_bf16 v[48:63], v[4:7], v[0:3], 0
	ds_read_b64 v[194:195], v16 offset:544
	ds_read_b64 v[196:197], v16 offset:560
	v_sub_f32_e32 v4, v64, v179
	v_exp_f32_e32 v204, v4
	v_sub_f32_e32 v4, v65, v179
	v_exp_f32_e32 v205, v4
	v_sub_f32_e32 v4, v66, v179
	v_exp_f32_e32 v206, v4
	v_sub_f32_e32 v4, v67, v179
	v_exp_f32_e32 v207, v4
	v_sub_f32_e32 v4, v68, v179
	v_sub_f32_e32 v64, v70, v179
	v_exp_f32_e32 v68, v4
	v_sub_f32_e32 v4, v69, v179
	v_exp_f32_e32 v70, v64
	v_sub_f32_e32 v64, v71, v179
	v_exp_f32_e32 v69, v4
	v_exp_f32_e32 v71, v64
	v_cvt_pk_bf16_f32 v64, v204, v205
	v_cvt_pk_bf16_f32 v65, v206, v207
	v_cvt_pk_bf16_f32 v66, v68, v69
	v_cvt_pk_bf16_f32 v67, v70, v71
	s_waitcnt lgkmcnt(10)
	v_mfma_f32_32x32x16_bf16 v[32:47], v[8:11], v[0:3], 0
	v_mul_u32_u24_e32 v181, 0x90, v182
	s_cmp_lt_i32 s62, 1
	s_waitcnt lgkmcnt(8)
	v_mfma_f32_32x32x16_bf16 v[16:31], v[12:15], v[0:3], 0
	s_waitcnt lgkmcnt(6)
	v_mfma_f32_32x32x16_bf16 v[0:15], v[76:79], v[0:3], 0
	v_mfma_f32_32x32x16_bf16 v[48:63], v[72:75], v[64:67], v[48:63]
	v_add_f32_e32 v72, 0, v180
	v_add_f32_e32 v72, v185, v72
	v_add_f32_e32 v72, v198, v72
	v_add_f32_e32 v72, v199, v72
	v_add_f32_e32 v72, v200, v72
	v_add_f32_e32 v72, v201, v72
	v_add_f32_e32 v72, v202, v72
	v_add_f32_e32 v72, v203, v72
	v_add_f32_e32 v72, v204, v72
	s_waitcnt lgkmcnt(4)
	v_mfma_f32_32x32x16_bf16 v[32:47], v[186:189], v[64:67], v[32:47]
	v_add_f32_e32 v72, v205, v72
	v_add_f32_e32 v72, v206, v72
	v_add_f32_e32 v72, v207, v72
	v_add_f32_e32 v68, v68, v72
	v_add_f32_e32 v68, v69, v68
	v_add_f32_e32 v68, v70, v68
	v_add_f32_e32 v68, v71, v68
	s_waitcnt lgkmcnt(2)
	v_mfma_f32_32x32x16_bf16 v[16:31], v[190:193], v[64:67], v[16:31]
	v_add_f32_e32 v180, 0, v68
	s_waitcnt lgkmcnt(0)
	v_mfma_f32_32x32x16_bf16 v[0:15], v[194:197], v[64:67], v[0:15]
	s_cbranch_scc1 .LBB0_453
	ds_read_b128 v[64:67], v183 offset:12800
	ds_read_b128 v[186:189], v183 offset:12832
	ds_read_b128 v[190:193], v183 offset:12864
	ds_read_b128 v[194:197], v183 offset:12896
	ds_read_b128 v[198:201], v183 offset:12928
	ds_read_b128 v[202:205], v183 offset:12960
	s_cmp_lg_u32 s62, 32
	s_waitcnt lgkmcnt(5)
	v_mfma_f32_32x32x16_bf16 v[64:79], v[64:67], v[80:83], 0
	ds_read_b128 v[206:209], v183 offset:12992
	s_waitcnt lgkmcnt(5)
	v_mfma_f32_32x32x16_bf16 v[64:79], v[186:189], v[84:87], v[64:79]
	ds_read_b128 v[186:189], v183 offset:13024
	s_waitcnt lgkmcnt(5)
	v_mfma_f32_32x32x16_bf16 v[64:79], v[190:193], v[88:91], v[64:79]
	ds_read_b128 v[190:193], v183 offset:13056
	s_waitcnt lgkmcnt(5)
	v_mfma_f32_32x32x16_bf16 v[64:79], v[194:197], v[92:95], v[64:79]
	ds_read_b128 v[194:197], v183 offset:13088
	s_waitcnt lgkmcnt(5)
	v_mfma_f32_32x32x16_bf16 v[64:79], v[198:201], v[96:99], v[64:79]
	ds_read_b128 v[198:201], v183 offset:13120
	s_waitcnt lgkmcnt(5)
	v_mfma_f32_32x32x16_bf16 v[64:79], v[202:205], v[100:103], v[64:79]
	ds_read_b128 v[202:205], v183 offset:13152
	s_waitcnt lgkmcnt(5)
	v_mfma_f32_32x32x16_bf16 v[64:79], v[206:209], v[104:107], v[64:79]
	s_waitcnt lgkmcnt(4)
	v_mfma_f32_32x32x16_bf16 v[64:79], v[186:189], v[108:111], v[64:79]
	s_waitcnt lgkmcnt(3)
	v_mfma_f32_32x32x16_bf16 v[64:79], v[190:193], v[112:115], v[64:79]
	s_waitcnt lgkmcnt(2)
	v_mfma_f32_32x32x16_bf16 v[64:79], v[194:197], v[116:119], v[64:79]
	s_waitcnt lgkmcnt(1)
	v_mfma_f32_32x32x16_bf16 v[64:79], v[198:201], v[120:123], v[64:79]
	s_waitcnt lgkmcnt(0)
	v_mfma_f32_32x32x16_bf16 v[64:79], v[202:205], v[124:127], v[64:79]
	s_cbranch_scc1 .LBB0_452
	s_nop 10
	v_cndmask_b32_e32 v183, v64, v163, vcc
	v_cndmask_b32_e64 v65, v163, v65, s[6:7]
	v_cndmask_b32_e64 v64, v183, v64, s[6:7]
	v_cndmask_b32_e64 v66, v66, v163, s[8:9]
	v_cndmask_b32_e64 v67, v67, v163, s[10:11]
	v_cndmask_b32_e64 v68, v68, v163, s[12:13]
	v_cndmask_b32_e64 v69, v69, v163, s[14:15]
	v_cndmask_b32_e64 v70, v70, v163, s[16:17]
	v_cndmask_b32_e64 v71, v71, v163, s[18:19]
	v_cndmask_b32_e64 v72, v72, v163, s[20:21]
	v_cndmask_b32_e64 v73, v73, v163, s[22:23]
	v_cndmask_b32_e64 v74, v74, v163, s[24:25]
	v_cndmask_b32_e64 v75, v75, v163, s[26:27]
	v_cndmask_b32_e64 v76, v76, v163, s[28:29]
	v_cndmask_b32_e64 v77, v77, v163, s[30:31]
	v_cndmask_b32_e64 v78, v78, v163, s[34:35]
	v_cndmask_b32_e64 v79, v79, v163, s[36:37]
; #define MFMA(a, b, c) __builtin_amdgcn_mfma_f32_32x32x16_bf16((a), (b), (c), 0, 0, 0)
; DI void attn_item(const Params& p, int bh, int qb, unsigned char* smem) {
;     ...
;             float ls = 0.f;
; #pragma unroll
;             for (int e = 0; e < 16; ++e) { const float pv = __builtin_amdgcn_exp2f(sc[e] - m_run); sc[e] = pv; ls += pv; }
;             l_run += ls;
;             bf16x8 pf[2]; pf[0] = pack8<0>(sc); pf[1] = pack8<1>(sc);
;             {
;                 bf16x8 vfr[2][4];
; #pragma unroll
;                 for (int s = 0; s < 2; ++s)
; #pragma unroll
;                     for (int t = 0; t < 4; ++t) vfr[s][t] = ld_frag_perm(sV + (t * 32 + r) * 72 + 16 * s + 4 * h);
; #pragma unroll
;                 for (int s = 0; s < 2; ++s)
; #pragma unroll
;                     for (int t = 0; t < 4; ++t) O[t] = MFMA(vfr[s][t], pf[s], O[t]);
;                 __builtin_amdgcn_sched_group_barrier(0x100, 8, 0);
; #pragma unroll
;                 for (int q = 0; q < 4; ++q) { __builtin_amdgcn_sched_group_barrier(0x008, 1, 0); __builtin_amdgcn_sched_group_barrier(0x100, 2, 0); }
;                 __builtin_amdgcn_sched_group_barrier(0x008, 4, 0);
;             }
.LBB0_452:
	s_nop 10
	v_sub_f32_e32 v64, v64, v179
	v_exp_f32_e32 v183, v64
	v_sub_f32_e32 v64, v65, v179
	v_exp_f32_e32 v212, v64
	v_sub_f32_e32 v64, v66, v179
	v_exp_f32_e32 v213, v64
	v_sub_f32_e32 v64, v67, v179
	v_exp_f32_e32 v214, v64
	v_sub_f32_e32 v64, v68, v179
	v_exp_f32_e32 v215, v64
	v_sub_f32_e32 v64, v69, v179
	v_add_u32_e32 v196, v184, v181
	v_exp_f32_e32 v216, v64
	v_sub_f32_e32 v64, v70, v179
	v_add_u32_e32 v184, 0x6000, v196
	v_exp_f32_e32 v217, v64
	v_sub_f32_e32 v64, v71, v179
	ds_read_b64 v[68:69], v184 offset:1088
	ds_read_b64 v[70:71], v184 offset:1104
	v_add_u32_e32 v200, 0x7000, v196
	v_add_u32_e32 v204, 0x8800, v196
	v_add_u32_e32 v208, 0x9800, v196
	ds_read_b64 v[188:189], v200 offset:1600
	ds_read_b64 v[190:191], v200 offset:1616
	ds_read_b64 v[192:193], v204 offset:64
	ds_read_b64 v[194:195], v204 offset:80
	ds_read_b64 v[196:197], v208 offset:576
	ds_read_b64 v[198:199], v208 offset:592
	v_exp_f32_e32 v218, v64
	v_cvt_pk_bf16_f32 v64, v183, v212
	v_cvt_pk_bf16_f32 v65, v213, v214
	v_cvt_pk_bf16_f32 v66, v215, v216
	v_cvt_pk_bf16_f32 v67, v217, v218
	ds_read_b64 v[186:187], v184 offset:1136
	ds_read_b64 v[184:185], v184 offset:1120
	ds_read_b64 v[202:203], v200 offset:1648
	ds_read_b64 v[200:201], v200 offset:1632
	ds_read_b64 v[206:207], v204 offset:112
	ds_read_b64 v[204:205], v204 offset:96
	s_waitcnt lgkmcnt(12)
	v_mfma_f32_32x32x16_bf16 v[48:63], v[68:71], v[64:67], v[48:63]
	ds_read_b64 v[210:211], v208 offset:624
	ds_read_b64 v[208:209], v208 offset:608
	v_sub_f32_e32 v68, v72, v179
	v_sub_f32_e32 v72, v76, v179
	v_add_f32_e32 v76, 0, v183
	v_add_f32_e32 v76, v212, v76
	v_add_f32_e32 v76, v213, v76
	v_sub_f32_e32 v69, v73, v179
	v_sub_f32_e32 v70, v74, v179
	s_waitcnt lgkmcnt(12)
	v_mfma_f32_32x32x16_bf16 v[32:47], v[188:191], v[64:67], v[32:47]
	v_sub_f32_e32 v71, v75, v179
	v_sub_f32_e32 v73, v77, v179
	v_sub_f32_e32 v74, v78, v179
	v_add_f32_e32 v76, v214, v76
	v_exp_f32_e32 v68, v68
	v_exp_f32_e32 v69, v69
	v_exp_f32_e32 v70, v70
	s_waitcnt lgkmcnt(10)
	v_mfma_f32_32x32x16_bf16 v[16:31], v[192:195], v[64:67], v[16:31]
	v_exp_f32_e32 v71, v71
	v_exp_f32_e32 v72, v72
	v_exp_f32_e32 v73, v73
	v_exp_f32_e32 v74, v74
	v_add_f32_e32 v76, v215, v76
	v_add_f32_e32 v76, v216, v76
	v_add_f32_e32 v76, v217, v76
	s_waitcnt lgkmcnt(8)
	v_mfma_f32_32x32x16_bf16 v[0:15], v[196:199], v[64:67], v[0:15]
	v_sub_f32_e32 v64, v79, v179
	v_exp_f32_e32 v75, v64
	v_add_f32_e32 v76, v218, v76
	v_cvt_pk_bf16_f32 v64, v68, v69
	v_cvt_pk_bf16_f32 v65, v70, v71
	v_cvt_pk_bf16_f32 v66, v72, v73
	v_cvt_pk_bf16_f32 v67, v74, v75
	v_add_f32_e32 v68, v68, v76
	v_add_f32_e32 v68, v69, v68
	s_waitcnt lgkmcnt(6)
	v_mfma_f32_32x32x16_bf16 v[48:63], v[184:187], v[64:67], v[48:63]
	v_add_f32_e32 v68, v70, v68
	v_add_f32_e32 v68, v71, v68
	v_add_f32_e32 v68, v72, v68
	v_add_f32_e32 v68, v73, v68
	v_add_f32_e32 v68, v74, v68
	v_add_f32_e32 v68, v75, v68
	v_add_f32_e32 v180, v180, v68
	s_waitcnt lgkmcnt(4)
	v_mfma_f32_32x32x16_bf16 v[32:47], v[200:203], v[64:67], v[32:47]
	s_waitcnt lgkmcnt(2)
	v_mfma_f32_32x32x16_bf16 v[16:31], v[204:207], v[64:67], v[16:31]
	s_waitcnt lgkmcnt(0)
	v_mfma_f32_32x32x16_bf16 v[0:15], v[208:211], v[64:67], v[0:15]

; #define MFMA(a, b, c) __builtin_amdgcn_mfma_f32_32x32x16_bf16((a), (b), (c), 0, 0, 0)
; DI void attn_item(const Params& p, int bh, int qb, unsigned char* smem) {
;     ...
;             float ls = 0.f;
; #pragma unroll
;             for (int e = 0; e < 16; ++e) { const float pv = __builtin_amdgcn_exp2f(sc[e] - m_run); sc[e] = pv; ls += pv; }
;             l_run += ls;
;             bf16x8 pf[2]; pf[0] = pack8<0>(sc); pf[1] = pack8<1>(sc);
;             {
;                 bf16x8 vfr[2][4];
; #pragma unroll
;                 for (int s = 0; s < 2; ++s)
; #pragma unroll
;                     for (int t = 0; t < 4; ++t) vfr[s][t] = ld_frag_perm(sV + (t * 32 + r) * 72 + 16 * s + 4 * h);
; #pragma unroll
;                 for (int s = 0; s < 2; ++s)
; #pragma unroll
;                     for (int t = 0; t < 4; ++t) O[t] = MFMA(vfr[s][t], pf[s], O[t]);
;                 __builtin_amdgcn_sched_group_barrier(0x100, 8, 0);
; #pragma unroll
;                 for (int q = 0; q < 4; ++q) { __builtin_amdgcn_sched_group_barrier(0x008, 1, 0); __builtin_amdgcn_sched_group_barrier(0x100, 2, 0); }
;                 __builtin_amdgcn_sched_group_barrier(0x008, 4, 0);
;             }
.LBB0_454:
	s_nop 5
	v_sub_f32_e32 v64, v64, v179
	s_nop 3
	v_exp_f32_e32 v64, v64
	v_sub_f32_e32 v65, v65, v179
	v_exp_f32_e32 v65, v65
	v_sub_f32_e32 v66, v66, v179
	v_exp_f32_e32 v66, v66
	v_sub_f32_e32 v67, v67, v179
	v_exp_f32_e32 v67, v67
	v_sub_f32_e32 v68, v68, v179
	v_add_f32_e32 v184, 0, v64
	v_exp_f32_e32 v68, v68
	v_sub_f32_e32 v69, v69, v179
	v_add_f32_e32 v184, v65, v184
	v_exp_f32_e32 v69, v69
	v_sub_f32_e32 v70, v70, v179
	v_add_f32_e32 v184, v66, v184
	v_exp_f32_e32 v70, v70
	v_sub_f32_e32 v71, v71, v179
	v_add_f32_e32 v184, v67, v184
	v_exp_f32_e32 v71, v71
	v_sub_f32_e32 v72, v72, v179
	v_add_f32_e32 v184, v68, v184
	v_exp_f32_e32 v72, v72
	v_sub_f32_e32 v73, v73, v179
	v_add_f32_e32 v184, v69, v184
	v_exp_f32_e32 v73, v73
	v_sub_f32_e32 v74, v74, v179
	v_add_f32_e32 v184, v70, v184
	v_exp_f32_e32 v74, v74
	v_sub_f32_e32 v75, v75, v179
	v_add_f32_e32 v184, v71, v184
	v_exp_f32_e32 v75, v75
	v_sub_f32_e32 v76, v76, v179
	v_add_f32_e32 v184, v72, v184
	v_exp_f32_e32 v76, v76
	v_sub_f32_e32 v77, v77, v179
	v_add_f32_e32 v184, v73, v184
	v_exp_f32_e32 v77, v77
	v_sub_f32_e32 v78, v78, v179
	v_add_f32_e32 v184, v74, v184
	v_exp_f32_e32 v78, v78
	v_sub_f32_e32 v79, v79, v179
	v_add_f32_e32 v184, v75, v184
	v_exp_f32_e32 v79, v79
	v_add_f32_e32 v184, v76, v184
	v_add_f32_e32 v184, v77, v184
	v_add_u32_e32 v183, v183, v181
	v_add_f32_e32 v184, v78, v184
	v_cvt_pk_bf16_f32 v64, v64, v65
	v_cvt_pk_bf16_f32 v65, v66, v67
	v_cvt_pk_bf16_f32 v67, v70, v71
	v_cvt_pk_bf16_f32 v70, v76, v77
	v_add_u32_e32 v76, 0x6000, v183
	v_add_u32_e32 v196, 0x7000, v183
	v_add_u32_e32 v200, 0x8800, v183
	v_add_u32_e32 v183, 0x9800, v183
	v_add_f32_e32 v208, v79, v184
	v_cvt_pk_bf16_f32 v66, v68, v69
	v_cvt_pk_bf16_f32 v68, v72, v73
	v_cvt_pk_bf16_f32 v69, v74, v75
	ds_read_b64 v[72:73], v76 offset:1088
	ds_read_b64 v[74:75], v76 offset:1104
	ds_read_b64 v[184:185], v196 offset:1600
	ds_read_b64 v[186:187], v196 offset:1616
	ds_read_b64 v[188:189], v200 offset:64
	ds_read_b64 v[190:191], v200 offset:80
	ds_read_b64 v[192:193], v183 offset:576
	ds_read_b64 v[194:195], v183 offset:592
	v_cvt_pk_bf16_f32 v71, v78, v79
	ds_read_b64 v[78:79], v76 offset:1136
	ds_read_b64 v[76:77], v76 offset:1120
	ds_read_b64 v[198:199], v196 offset:1648
	ds_read_b64 v[196:197], v196 offset:1632
	ds_read_b64 v[202:203], v200 offset:112
	ds_read_b64 v[200:201], v200 offset:96
	s_waitcnt lgkmcnt(12)
	v_mfma_f32_32x32x16_bf16 v[48:63], v[72:75], v[64:67], v[48:63]
	ds_read_b64 v[204:205], v183 offset:608
	ds_read_b64 v[206:207], v183 offset:624
	v_add_f32_e32 v180, v180, v208
	s_waitcnt lgkmcnt(12)
	v_mfma_f32_32x32x16_bf16 v[32:47], v[184:187], v[64:67], v[32:47]
	s_waitcnt lgkmcnt(10)
	v_mfma_f32_32x32x16_bf16 v[16:31], v[188:191], v[64:67], v[16:31]
	s_waitcnt lgkmcnt(8)
	v_mfma_f32_32x32x16_bf16 v[0:15], v[192:195], v[64:67], v[0:15]
	s_waitcnt lgkmcnt(6)
	v_mfma_f32_32x32x16_bf16 v[48:63], v[76:79], v[68:71], v[48:63]
	s_waitcnt lgkmcnt(4)
	v_mfma_f32_32x32x16_bf16 v[32:47], v[196:199], v[68:71], v[32:47]
	s_waitcnt lgkmcnt(2)
	v_mfma_f32_32x32x16_bf16 v[16:31], v[200:203], v[68:71], v[16:31]
	s_waitcnt lgkmcnt(0)
	v_mfma_f32_32x32x16_bf16 v[0:15], v[204:207], v[68:71], v[0:15]

.LBB0_456:
	s_add_i32 s75, s74, 0x81
	s_cmp_ge_u32 s75, s63
	s_cbranch_scc1 .LBB0_458
	s_bitcmp1_b32 s75, 0
	s_cselect_b32 s75, 0xac00, 0
	s_add_i32 s75, s75, 0
	v_add3_u32 v64, s75, v169, v170
	s_waitcnt vmcnt(2)
	ds_write_b128 v64, v[128:131]
	v_add3_u32 v64, s75, v171, v172
	s_waitcnt vmcnt(1)
	ds_write_b128 v64, v[132:135]
	v_add3_u32 v64, s75, v173, v174
	s_waitcnt vmcnt(0)
	ds_write_b128 v64, v[136:139]
	v_lshl_add_u32 v64, v168, 1, s75
	v_add_u32_e32 v65, v64, v175
	v_add_u32_e32 v64, v64, v176
	v_add_u32_e32 v66, s98, v65
	v_subrev_u32_e32 v67, s98, v65
	v_add_u32_e32 v68, s98, v64
	v_subrev_u32_e32 v69, s98, v64
	ds_write_b64 v66, v[140:141] offset:25600
	ds_write_b64 v67, v[142:143] offset:25608
	ds_write_b64 v68, v[144:145] offset:25600
	ds_write_b64 v69, v[146:147] offset:25608

; #define MFMA(a, b, c) __builtin_amdgcn_mfma_f32_32x32x16_bf16((a), (b), (c), 0, 0, 0)
; DI void attn_item(const Params& p, int bh, int qb, unsigned char* smem) {
;     ...
;             float ls = 0.f;
; #pragma unroll
;             for (int e = 0; e < 16; ++e) { const float pv = __builtin_amdgcn_exp2f(sc[e] - m_run); sc[e] = pv; ls += pv; }
;             l_run += ls;
;             bf16x8 pf[2]; pf[0] = pack8<0>(sc); pf[1] = pack8<1>(sc);
;             {
;                 bf16x8 vfr[2][4];
; #pragma unroll
;                 for (int s = 0; s < 2; ++s)
; #pragma unroll
;                     for (int t = 0; t < 4; ++t) vfr[s][t] = ld_frag_perm(sV + (t * 32 + r) * 72 + 16 * s + 4 * h);
; #pragma unroll
;                 for (int s = 0; s < 2; ++s)
; #pragma unroll
;                     for (int t = 0; t < 4; ++t) O[t] = MFMA(vfr[s][t], pf[s], O[t]);
;                 __builtin_amdgcn_sched_group_barrier(0x100, 8, 0);
; #pragma unroll
;                 for (int q = 0; q < 4; ++q) { __builtin_amdgcn_sched_group_barrier(0x008, 1, 0); __builtin_amdgcn_sched_group_barrier(0x100, 2, 0); }
;                 __builtin_amdgcn_sched_group_barrier(0x008, 4, 0);
;             }
.LBB0_463:
	s_nop 10
	v_sub_f32_e32 v64, v64, v179
	v_exp_f32_e32 v64, v64
	v_sub_f32_e32 v65, v65, v179
	v_exp_f32_e32 v65, v65
	v_sub_f32_e32 v66, v66, v179
	v_exp_f32_e32 v66, v66
	v_sub_f32_e32 v67, v67, v179
	v_exp_f32_e32 v67, v67
	v_sub_f32_e32 v68, v68, v179
	v_add_f32_e32 v185, 0, v64
	v_exp_f32_e32 v68, v68
	v_sub_f32_e32 v69, v69, v179
	v_add_f32_e32 v185, v65, v185
	v_exp_f32_e32 v69, v69
	v_sub_f32_e32 v70, v70, v179
	v_add_f32_e32 v185, v66, v185
	v_exp_f32_e32 v70, v70
	v_sub_f32_e32 v71, v71, v179
	v_add_f32_e32 v185, v67, v185
	v_exp_f32_e32 v71, v71
	v_sub_f32_e32 v72, v72, v179
	v_add_f32_e32 v185, v68, v185
	v_exp_f32_e32 v72, v72
	v_sub_f32_e32 v73, v73, v179
	v_add_f32_e32 v185, v69, v185
	v_exp_f32_e32 v73, v73
	v_sub_f32_e32 v74, v74, v179
	v_add_f32_e32 v185, v70, v185
	v_exp_f32_e32 v74, v74
	v_sub_f32_e32 v75, v75, v179
	v_add_f32_e32 v185, v71, v185
	v_exp_f32_e32 v75, v75
	v_sub_f32_e32 v76, v76, v179
	v_sub_f32_e32 v77, v77, v179
	v_add_f32_e32 v185, v72, v185
	v_exp_f32_e32 v76, v76
	v_exp_f32_e32 v77, v77
	v_add_f32_e32 v185, v73, v185
	v_add_f32_e32 v185, v74, v185
	v_add_f32_e32 v185, v75, v185
	v_add_u32_e32 v194, v183, v181
	v_add_f32_e32 v185, v76, v185
	v_cvt_pk_bf16_f32 v64, v64, v65
	v_cvt_pk_bf16_f32 v65, v66, v67
	v_cvt_pk_bf16_f32 v67, v70, v71
	v_cvt_pk_bf16_f32 v70, v76, v77
	v_add_u32_e32 v76, 0x6000, v194
	v_add_u32_e32 v198, 0x7000, v194
	v_add_u32_e32 v202, 0x8800, v194
	v_add_u32_e32 v206, 0x9800, v194
	v_cvt_pk_bf16_f32 v66, v68, v69
	v_cvt_pk_bf16_f32 v68, v72, v73
	v_cvt_pk_bf16_f32 v69, v74, v75
	ds_read_b64 v[72:73], v76 offset:1024
	ds_read_b64 v[74:75], v76 offset:1040
	ds_read_b64 v[186:187], v198 offset:1536
	ds_read_b64 v[188:189], v198 offset:1552
	ds_read_b64 v[190:191], v202 offset:0
	ds_read_b64 v[192:193], v202 offset:16
	ds_read_b64 v[194:195], v206 offset:512
	ds_read_b64 v[196:197], v206 offset:528
	v_sub_f32_e32 v78, v78, v179
	v_exp_f32_e32 v78, v78
	v_sub_f32_e32 v79, v79, v179
	v_exp_f32_e32 v79, v79
	v_add_f32_e32 v185, v77, v185
	v_add_f32_e32 v185, v78, v185
	ds_read_b64 v[200:201], v198 offset:1584
	ds_read_b64 v[198:199], v198 offset:1568
	v_add_f32_e32 v185, v79, v185
	v_cvt_pk_bf16_f32 v71, v78, v79
	ds_read_b64 v[78:79], v76 offset:1072
	ds_read_b64 v[76:77], v76 offset:1056
	ds_read_b64 v[204:205], v202 offset:48
	ds_read_b64 v[202:203], v202 offset:32
	s_waitcnt lgkmcnt(12)
	v_mfma_f32_32x32x16_bf16 v[48:63], v[72:75], v[64:67], v[48:63]
	ds_read_b64 v[208:209], v206 offset:560
	ds_read_b64 v[206:207], v206 offset:544
	v_add_f32_e32 v180, v180, v185
	s_waitcnt lgkmcnt(12)
	v_mfma_f32_32x32x16_bf16 v[32:47], v[186:189], v[64:67], v[32:47]
	s_waitcnt lgkmcnt(10)
	v_mfma_f32_32x32x16_bf16 v[16:31], v[190:193], v[64:67], v[16:31]
	s_waitcnt lgkmcnt(8)
	v_mfma_f32_32x32x16_bf16 v[0:15], v[194:197], v[64:67], v[0:15]
	s_waitcnt lgkmcnt(4)
	v_mfma_f32_32x32x16_bf16 v[48:63], v[76:79], v[68:71], v[48:63]
	v_mfma_f32_32x32x16_bf16 v[32:47], v[198:201], v[68:71], v[32:47]
	s_waitcnt lgkmcnt(2)
	v_mfma_f32_32x32x16_bf16 v[16:31], v[202:205], v[68:71], v[16:31]
	s_waitcnt lgkmcnt(0)
	v_mfma_f32_32x32x16_bf16 v[0:15], v[206:209], v[68:71], v[0:15]

; __global__ void __launch_bounds__(512, 2) hymba_fwd(Params pin) {
;     extern __shared__ __attribute__((aligned(16))) unsigned char smem[];
;     Params p = pin;
;     p.wave8 = __builtin_amdgcn_readfirstlane((int)(threadIdx.x >> 6));
;     p.wave_u = p.wave8 & 3;
;     const int half = p.wave8 >> 2;
;     p.vb = blockIdx.x * 2 + half; p.vg = gridDim.x * 2;
;     unsigned char* smem_h = smem + half * HALF_LDS;
;     int* s_item = (int*)(smem + 2 * HALF_LDS);
;     phase0(p, smem_h);
;     cg::this_grid().sync();
;     phase1(p, smem);
;     grid_barrier(p, 1);
;     phase2(p, smem_h);
;     grid_barrier(p, 2);
;     phase3(p, smem_h, smem, s_item);
;     grid_barrier(p, 3);
;     phase_norm(p);
;     grid_barrier(p, 4);
;     phase4(p, smem);
; }
	.amdhsa_kernel _Z9hymba_fwd6Params
		.amdhsa_group_segment_fixed_size 0
		.amdhsa_private_segment_fixed_size 0
		.amdhsa_kernarg_size 408
		.amdhsa_user_sgpr_count 2
		.amdhsa_user_sgpr_dispatch_ptr 0
		.amdhsa_user_sgpr_queue_ptr 0
		.amdhsa_user_sgpr_kernarg_segment_ptr 1
		.amdhsa_user_sgpr_dispatch_id 0
		.amdhsa_user_sgpr_kernarg_preload_length 0
		.amdhsa_user_sgpr_kernarg_preload_offset 0
		.amdhsa_user_sgpr_private_segment_size 0
		.amdhsa_uses_dynamic_stack 0
		.amdhsa_enable_private_segment 0
		.amdhsa_system_sgpr_workgroup_id_x 1
		.amdhsa_system_sgpr_workgroup_id_y 0
		.amdhsa_system_sgpr_workgroup_id_z 0
		.amdhsa_system_sgpr_workgroup_info 0
		.amdhsa_system_vgpr_workitem_id 2
		.amdhsa_next_free_vgpr 247
		.amdhsa_next_free_sgpr 102
		.amdhsa_accum_offset 248
		.amdhsa_reserve_vcc 1
		.amdhsa_float_round_mode_32 0
		.amdhsa_float_round_mode_16_64 0
		.amdhsa_float_denorm_mode_32 3
		.amdhsa_float_denorm_mode_16_64 3
		.amdhsa_dx10_clamp 1
		.amdhsa_ieee_mode 1
		.amdhsa_fp16_overflow 0
		.amdhsa_tg_split 0
		.amdhsa_exception_fp_ieee_invalid_op 0
		.amdhsa_exception_fp_denorm_src 0
		.amdhsa_exception_fp_ieee_div_zero 0
		.amdhsa_exception_fp_ieee_overflow 0
		.amdhsa_exception_fp_ieee_underflow 0
		.amdhsa_exception_fp_ieee_inexact 0
		.amdhsa_exception_int_div_zero 0
	.end_amdhsa_kernel

; __global__ void __launch_bounds__(512, 2) hymba_fwd(Params pin) {
;     extern __shared__ __attribute__((aligned(16))) unsigned char smem[];
;     Params p = pin;
;     p.wave8 = __builtin_amdgcn_readfirstlane((int)(threadIdx.x >> 6));
;     p.wave_u = p.wave8 & 3;
;     const int half = p.wave8 >> 2;
;     p.vb = blockIdx.x * 2 + half; p.vg = gridDim.x * 2;
;     unsigned char* smem_h = smem + half * HALF_LDS;
;     int* s_item = (int*)(smem + 2 * HALF_LDS);
;     phase0(p, smem_h);
;     cg::this_grid().sync();
;     phase1(p, smem);
;     grid_barrier(p, 1);
;     phase2(p, smem_h);
;     grid_barrier(p, 2);
;     phase3(p, smem_h, smem, s_item);
;     grid_barrier(p, 3);
;     phase_norm(p);
;     grid_barrier(p, 4);
;     phase4(p, smem);
; }
amdhsa.kernels:
  - .agpr_count:     0
    .args:
      - .offset:         0
        .size:           152
        .value_kind:     by_value
      - .offset:         152
        .size:           4
        .value_kind:     hidden_block_count_x
      - .offset:         156
        .size:           4
        .value_kind:     hidden_block_count_y
      - .offset:         160
        .size:           4
        .value_kind:     hidden_block_count_z
      - .offset:         164
        .size:           2
        .value_kind:     hidden_group_size_x
      - .offset:         166
        .size:           2
        .value_kind:     hidden_group_size_y
      - .offset:         168
        .size:           2
        .value_kind:     hidden_group_size_z
      - .offset:         170
        .size:           2
        .value_kind:     hidden_remainder_x
      - .offset:         172
        .size:           2
        .value_kind:     hidden_remainder_y
      - .offset:         174
        .size:           2
        .value_kind:     hidden_remainder_z
      - .offset:         192
        .size:           8
        .value_kind:     hidden_global_offset_x
      - .offset:         200
        .size:           8
        .value_kind:     hidden_global_offset_y
      - .offset:         208
        .size:           8
        .value_kind:     hidden_global_offset_z
      - .offset:         216
        .size:           2
        .value_kind:     hidden_grid_dims
      - .offset:         240
        .size:           8
        .value_kind:     hidden_multigrid_sync_arg
      - .offset:         272
        .size:           4
        .value_kind:     hidden_dynamic_lds_size
    .group_segment_fixed_size: 0
    .kernarg_segment_align: 8
    .kernarg_segment_size: 408
    .language:       OpenCL C
    .language_version:
      - 2
      - 0
    .max_flat_workgroup_size: 512
    .name:           _Z9hymba_fwd6Params
    .private_segment_fixed_size: 0
    .sgpr_count:     108
    .sgpr_spill_count: 167
    .symbol:         _Z9hymba_fwd6Params.kd
    .uniform_work_group_size: 1
    .uses_dynamic_stack: false
    .vgpr_count:     247
    .vgpr_spill_count: 0
    .wavefront_size: 64
